# speedup vs baseline: 1.0006x; 1.0006x over previous
; template <int TRM>
; DI void inproj_epi(const acc4 (&acc)[2][2][4][2], int wr, int wc, int fr, int fq, int pm, int pn, u16* R, u16* T, float* CB, u32* KMAX2, const float* bfp, char* lds) {
;     ...
;           for (int bj = 0; bj < 2; ++bj) {
;             const int cbase = pn * 256 + bj * 128 + wc * 32;
;             if (TRM & (1 << bj)) {
; #pragma unroll
;               for (int ai = 0; ai < 2; ++ai)
; #pragma unroll
;                 for (int m = 0; m < 4; ++m) {
;                   const int row = pm * 256 + ai * 128 + wr * 64 + m * 16 + fr;
; #pragma unroll
;                   for (int n = 0; n < 2; ++n) {
;                     const int col = cbase + n * 16 + fq * 4;
;                     const acc4 v = acc[ai][bj][m][n];
;                     u32x2 pk = {pack2(v[0], v[1]), pack2(v[2], v[3])};
;                     *reinterpret_cast<u32x2*>(R + (row * LDR + col)) = pk;
;                     if (col == RC_F) {
; #pragma unroll
;                       for (int j = 0; j < 4; ++j) CB[(size_t)j * SEQ + row] = v[j] + bfp[j];
;                     }
;                   }
.LBB0_248:
	global_load_dwordx4 v[200:203], v1, s[26:27]
	s_lshl_b32 s10, s11, 5
	s_bitset1_b32 s10, 11
	v_add_u32_e32 v130, s22, v130
	v_lshlrev_b32_e32 v132, 2, v131
	s_movk_i32 s11, 0x880
	v_or_b32_e32 v133, s10, v132
	v_mul_lo_u32 v134, v130, s11
	v_add_u32_e32 v138, v133, v134
	v_ashrrev_i32_e32 v139, 31, v138
	s_movk_i32 s11, 0x80c
	v_cvt_pk_bf16_f32 v136, v126, v127
	v_cvt_pk_bf16_f32 v137, v128, v129
	v_lshl_add_u64 v[138:139], v[138:139], 1, s[82:83]
	v_cmp_eq_u32_e64 s[44:45], s11, v133
	s_waitcnt vmcnt(0)
	global_store_dwordx2 v[138:139], v[136:137], off
	s_and_saveexec_b64 s[46:47], s[44:45]
	s_cbranch_execz .LBB0_250
	v_readlane_b32 s12, v254, 20
	v_ashrrev_i32_e32 v131, 31, v130
	v_readlane_b32 s13, v254, 21
	s_nop 1
	v_lshl_add_u64 v[136:137], v[130:131], 2, s[12:13]
	v_mov_b32_e32 v131, v200
	v_add_f32_e32 v126, v126, v131
	global_store_dword v[136:137], v126, off
	v_mov_b32_e32 v126, v201
	v_add_f32_e32 v131, v127, v126
	v_add_co_u32_e32 v126, vcc, 0x10000, v136
	s_nop 1
	v_addc_co_u32_e32 v127, vcc, 0, v137, vcc
	global_store_dword v[126:127], v131, off
	v_mov_b32_e32 v126, v202
	v_add_f32_e32 v128, v128, v126
	v_add_co_u32_e32 v126, vcc, 0x20000, v136
	s_nop 1
	v_addc_co_u32_e32 v127, vcc, 0, v137, vcc
	global_store_dword v[126:127], v128, off
	v_mov_b32_e32 v126, v203
	v_add_f32_e32 v128, v129, v126
	v_add_co_u32_e32 v126, vcc, 0x30000, v136
	s_nop 1
	v_addc_co_u32_e32 v127, vcc, 0, v137, vcc
	global_store_dword v[126:127], v128, off
.LBB0_250:
	s_or_b64 exec, exec, s[46:47]
	v_or_b32_e32 v126, 16, v133
	v_cvt_pk_bf16_f32 v122, v122, v123
	v_cvt_pk_bf16_f32 v123, v124, v125
	v_add_u32_e32 v124, v126, v134
	v_ashrrev_i32_e32 v125, 31, v124
	v_lshl_add_u64 v[124:125], v[124:125], 1, s[82:83]
	global_store_dwordx2 v[124:125], v[122:123], off
	v_add_u32_e32 v122, 0x8800, v134
	v_add_u32_e32 v128, v122, v133
	v_ashrrev_i32_e32 v129, 31, v128
	v_cvt_pk_bf16_f32 v124, v118, v119
	v_cvt_pk_bf16_f32 v125, v120, v121
	v_lshl_add_u64 v[128:129], v[128:129], 1, s[82:83]
	global_store_dwordx2 v[128:129], v[124:125], off
	s_and_saveexec_b64 s[46:47], s[44:45]
	s_cbranch_execz .LBB0_252
	v_mov_b32_e32 v123, v200
	v_or_b32_e32 v124, 16, v130
	v_readlane_b32 s12, v254, 20
	v_ashrrev_i32_e32 v125, 31, v124
	v_readlane_b32 s13, v254, 21
	v_add_f32_e32 v118, v118, v123
	v_lshl_add_u64 v[124:125], v[124:125], 2, s[12:13]
	global_store_dword v[124:125], v118, off
	v_mov_b32_e32 v118, v201
	v_add_f32_e32 v123, v119, v118
	v_add_co_u32_e32 v118, vcc, 0x10000, v124
	s_nop 1
	v_addc_co_u32_e32 v119, vcc, 0, v125, vcc
	global_store_dword v[118:119], v123, off
	v_mov_b32_e32 v118, v202
	v_add_f32_e32 v120, v120, v118
	v_add_co_u32_e32 v118, vcc, 0x20000, v124
	s_nop 1
	v_addc_co_u32_e32 v119, vcc, 0, v125, vcc
	global_store_dword v[118:119], v120, off
	v_mov_b32_e32 v118, v203
	v_add_f32_e32 v120, v121, v118
	v_add_co_u32_e32 v118, vcc, 0x30000, v124
	s_nop 1
	v_addc_co_u32_e32 v119, vcc, 0, v125, vcc
	global_store_dword v[118:119], v120, off
.LBB0_252:
	s_or_b64 exec, exec, s[46:47]
	v_cvt_pk_bf16_f32 v114, v114, v115
	v_cvt_pk_bf16_f32 v115, v116, v117
	v_add_u32_e32 v116, v126, v122
	v_ashrrev_i32_e32 v117, 31, v116
	v_lshl_add_u64 v[116:117], v[116:117], 1, s[82:83]
	global_store_dwordx2 v[116:117], v[114:115], off
	v_add_u32_e32 v114, 0x8800, v122
	v_add_u32_e32 v118, v114, v133
	v_ashrrev_i32_e32 v119, 31, v118
	v_cvt_pk_bf16_f32 v116, v110, v111
	v_cvt_pk_bf16_f32 v117, v112, v113
	v_lshl_add_u64 v[118:119], v[118:119], 1, s[82:83]
	global_store_dwordx2 v[118:119], v[116:117], off
	s_and_saveexec_b64 s[46:47], s[44:45]
	s_cbranch_execz .LBB0_254
	v_mov_b32_e32 v115, v200
	v_or_b32_e32 v116, 32, v130
	v_readlane_b32 s12, v254, 20
	v_ashrrev_i32_e32 v117, 31, v116
	v_readlane_b32 s13, v254, 21
	v_add_f32_e32 v110, v110, v115
	v_lshl_add_u64 v[116:117], v[116:117], 2, s[12:13]
	global_store_dword v[116:117], v110, off
	v_mov_b32_e32 v110, v201
	v_add_f32_e32 v115, v111, v110
	v_add_co_u32_e32 v110, vcc, 0x10000, v116
	s_nop 1
	v_addc_co_u32_e32 v111, vcc, 0, v117, vcc
	global_store_dword v[110:111], v115, off
	v_mov_b32_e32 v110, v202
	v_add_f32_e32 v112, v112, v110
	v_add_co_u32_e32 v110, vcc, 0x20000, v116
	s_nop 1
	v_addc_co_u32_e32 v111, vcc, 0, v117, vcc
	global_store_dword v[110:111], v112, off
	v_mov_b32_e32 v110, v203
	v_add_f32_e32 v112, v113, v110
	v_add_co_u32_e32 v110, vcc, 0x30000, v116
	s_nop 1
	v_addc_co_u32_e32 v111, vcc, 0, v117, vcc
	global_store_dword v[110:111], v112, off
.LBB0_254:
	s_or_b64 exec, exec, s[46:47]
	v_cvt_pk_bf16_f32 v106, v106, v107
	v_cvt_pk_bf16_f32 v107, v108, v109
	v_add_u32_e32 v108, v126, v114
	v_ashrrev_i32_e32 v109, 31, v108
	v_lshl_add_u64 v[108:109], v[108:109], 1, s[82:83]
	global_store_dwordx2 v[108:109], v[106:107], off
	v_add_u32_e32 v106, 0x8800, v114
	v_add_u32_e32 v110, v106, v133
	v_ashrrev_i32_e32 v111, 31, v110
	v_cvt_pk_bf16_f32 v108, v102, v103
	v_cvt_pk_bf16_f32 v109, v104, v105
	v_lshl_add_u64 v[110:111], v[110:111], 1, s[82:83]
	global_store_dwordx2 v[110:111], v[108:109], off
	s_and_saveexec_b64 s[46:47], s[44:45]
	s_cbranch_execz .LBB0_256
	v_mov_b32_e32 v107, v200
	v_or_b32_e32 v108, 48, v130
	v_readlane_b32 s12, v254, 20
	v_ashrrev_i32_e32 v109, 31, v108
	v_readlane_b32 s13, v254, 21
	v_add_f32_e32 v102, v102, v107
	v_lshl_add_u64 v[108:109], v[108:109], 2, s[12:13]
	global_store_dword v[108:109], v102, off
	v_mov_b32_e32 v102, v201
	v_add_f32_e32 v107, v103, v102
	v_add_co_u32_e32 v102, vcc, 0x10000, v108
	s_nop 1
	v_addc_co_u32_e32 v103, vcc, 0, v109, vcc
	global_store_dword v[102:103], v107, off
	v_mov_b32_e32 v102, v202
	v_add_f32_e32 v104, v104, v102
	v_add_co_u32_e32 v102, vcc, 0x20000, v108
	s_nop 1
	v_addc_co_u32_e32 v103, vcc, 0, v109, vcc
	global_store_dword v[102:103], v104, off
	v_mov_b32_e32 v102, v203
	v_add_f32_e32 v104, v105, v102
	v_add_co_u32_e32 v102, vcc, 0x30000, v108
	s_nop 1
	v_addc_co_u32_e32 v103, vcc, 0, v109, vcc
	global_store_dword v[102:103], v104, off
; template <int TRM>
; DI void inproj_epi(const acc4 (&acc)[2][2][4][2], int wr, int wc, int fr, int fq, int pm, int pn, u16* R, u16* T, float* CB, u32* KMAX2, const float* bfp, char* lds) {
;     ...
;           for (int bj = 0; bj < 2; ++bj) {
;             const int cbase = pn * 256 + bj * 128 + wc * 32;
;             if (TRM & (1 << bj)) {
; #pragma unroll
;               for (int ai = 0; ai < 2; ++ai)
; #pragma unroll
;                 for (int m = 0; m < 4; ++m) {
;                   const int row = pm * 256 + ai * 128 + wr * 64 + m * 16 + fr;
; #pragma unroll
;                   for (int n = 0; n < 2; ++n) {
;                     const int col = cbase + n * 16 + fq * 4;
;                     const acc4 v = acc[ai][bj][m][n];
;                     u32x2 pk = {pack2(v[0], v[1]), pack2(v[2], v[3])};
;                     *reinterpret_cast<u32x2*>(R + (row * LDR + col)) = pk;
;                     if (col == RC_F) {
; #pragma unroll
;                       for (int j = 0; j < 4; ++j) CB[(size_t)j * SEQ + row] = v[j] + bfp[j];
;                     }
;                   }
.LBB0_256:
	s_or_b64 exec, exec, s[46:47]
	v_cvt_pk_bf16_f32 v98, v98, v99
	v_cvt_pk_bf16_f32 v99, v100, v101
	v_add_u32_e32 v100, v126, v106
	v_ashrrev_i32_e32 v101, 31, v100
	v_lshl_add_u64 v[100:101], v[100:101], 1, s[82:83]
	global_store_dwordx2 v[100:101], v[98:99], off
	v_add_u32_e32 v98, 0x2a800, v106
	v_add_u32_e32 v102, v98, v133
	v_ashrrev_i32_e32 v103, 31, v102
	v_cvt_pk_bf16_f32 v100, v94, v95
	v_cvt_pk_bf16_f32 v101, v96, v97
	v_lshl_add_u64 v[102:103], v[102:103], 1, s[82:83]
	global_store_dwordx2 v[102:103], v[100:101], off
	s_and_saveexec_b64 s[46:47], s[44:45]
	s_cbranch_execz .LBB0_258
	v_mov_b32_e32 v99, v200
	v_add_u32_e32 v100, 0x80, v130
	v_readlane_b32 s12, v254, 20
	v_ashrrev_i32_e32 v101, 31, v100
	v_readlane_b32 s13, v254, 21
	v_add_f32_e32 v94, v94, v99
	v_lshl_add_u64 v[100:101], v[100:101], 2, s[12:13]
	global_store_dword v[100:101], v94, off
	v_mov_b32_e32 v94, v201
	v_add_f32_e32 v99, v95, v94
	v_add_co_u32_e32 v94, vcc, 0x10000, v100
	s_nop 1
	v_addc_co_u32_e32 v95, vcc, 0, v101, vcc
	global_store_dword v[94:95], v99, off
	v_mov_b32_e32 v94, v202
	v_add_f32_e32 v96, v96, v94
	v_add_co_u32_e32 v94, vcc, 0x20000, v100
	s_nop 1
	v_addc_co_u32_e32 v95, vcc, 0, v101, vcc
	global_store_dword v[94:95], v96, off
	v_mov_b32_e32 v94, v203
	v_add_f32_e32 v96, v97, v94
	v_add_co_u32_e32 v94, vcc, 0x30000, v100
	s_nop 1
	v_addc_co_u32_e32 v95, vcc, 0, v101, vcc
	global_store_dword v[94:95], v96, off
.LBB0_258:
	s_or_b64 exec, exec, s[46:47]
	v_cvt_pk_bf16_f32 v90, v90, v91
	v_cvt_pk_bf16_f32 v91, v92, v93
	v_add_u32_e32 v92, v126, v98
	v_ashrrev_i32_e32 v93, 31, v92
	v_lshl_add_u64 v[92:93], v[92:93], 1, s[82:83]
	global_store_dwordx2 v[92:93], v[90:91], off
	v_add_u32_e32 v90, 0x8800, v98
	v_add_u32_e32 v94, v90, v133
	v_ashrrev_i32_e32 v95, 31, v94
	v_cvt_pk_bf16_f32 v92, v86, v87
	v_cvt_pk_bf16_f32 v93, v88, v89
	v_lshl_add_u64 v[94:95], v[94:95], 1, s[82:83]
	global_store_dwordx2 v[94:95], v[92:93], off
	s_and_saveexec_b64 s[46:47], s[44:45]
	s_cbranch_execz .LBB0_260
	v_mov_b32_e32 v91, v200
	v_add_u32_e32 v92, 0x90, v130
	v_readlane_b32 s12, v254, 20
	v_ashrrev_i32_e32 v93, 31, v92
	v_readlane_b32 s13, v254, 21
	v_add_f32_e32 v86, v86, v91
	v_lshl_add_u64 v[92:93], v[92:93], 2, s[12:13]
	global_store_dword v[92:93], v86, off
	v_mov_b32_e32 v86, v201
	v_add_f32_e32 v91, v87, v86
	v_add_co_u32_e32 v86, vcc, 0x10000, v92
	s_nop 1
	v_addc_co_u32_e32 v87, vcc, 0, v93, vcc
	global_store_dword v[86:87], v91, off
	v_mov_b32_e32 v86, v202
	v_add_f32_e32 v88, v88, v86
	v_add_co_u32_e32 v86, vcc, 0x20000, v92
	s_nop 1
	v_addc_co_u32_e32 v87, vcc, 0, v93, vcc
	global_store_dword v[86:87], v88, off
	v_mov_b32_e32 v86, v203
	v_add_f32_e32 v88, v89, v86
	v_add_co_u32_e32 v86, vcc, 0x30000, v92
	s_nop 1
	v_addc_co_u32_e32 v87, vcc, 0, v93, vcc
	global_store_dword v[86:87], v88, off
.LBB0_260:
	s_or_b64 exec, exec, s[46:47]
	v_cvt_pk_bf16_f32 v82, v82, v83
	v_cvt_pk_bf16_f32 v83, v84, v85
	v_add_u32_e32 v84, v126, v90
	v_ashrrev_i32_e32 v85, 31, v84
	v_lshl_add_u64 v[84:85], v[84:85], 1, s[82:83]
	global_store_dwordx2 v[84:85], v[82:83], off
	v_add_u32_e32 v82, 0x8800, v90
	v_add_u32_e32 v86, v82, v133
	v_ashrrev_i32_e32 v87, 31, v86
	v_cvt_pk_bf16_f32 v84, v78, v79
	v_cvt_pk_bf16_f32 v85, v80, v81
	v_lshl_add_u64 v[86:87], v[86:87], 1, s[82:83]
	global_store_dwordx2 v[86:87], v[84:85], off
	s_and_saveexec_b64 s[46:47], s[44:45]
	s_cbranch_execz .LBB0_262
	v_mov_b32_e32 v83, v200
	v_add_u32_e32 v84, 0xa0, v130
	v_readlane_b32 s12, v254, 20
	v_ashrrev_i32_e32 v85, 31, v84
	v_readlane_b32 s13, v254, 21
	v_add_f32_e32 v78, v78, v83
	v_lshl_add_u64 v[84:85], v[84:85], 2, s[12:13]
	global_store_dword v[84:85], v78, off
	v_mov_b32_e32 v78, v201
	v_add_f32_e32 v83, v79, v78
	v_add_co_u32_e32 v78, vcc, 0x10000, v84
	s_nop 1
	v_addc_co_u32_e32 v79, vcc, 0, v85, vcc
	global_store_dword v[78:79], v83, off
	v_mov_b32_e32 v78, v202
	v_add_f32_e32 v80, v80, v78
	v_add_co_u32_e32 v78, vcc, 0x20000, v84
	s_nop 1
	v_addc_co_u32_e32 v79, vcc, 0, v85, vcc
	global_store_dword v[78:79], v80, off
	v_mov_b32_e32 v78, v203
	v_add_f32_e32 v80, v81, v78
	v_add_co_u32_e32 v78, vcc, 0x30000, v84
	s_nop 1
	v_addc_co_u32_e32 v79, vcc, 0, v85, vcc
	global_store_dword v[78:79], v80, off
.LBB0_262:
	s_or_b64 exec, exec, s[46:47]
	v_cvt_pk_bf16_f32 v74, v74, v75
	v_cvt_pk_bf16_f32 v75, v76, v77
	v_add_u32_e32 v76, v126, v82
	v_ashrrev_i32_e32 v77, 31, v76
	v_lshl_add_u64 v[76:77], v[76:77], 1, s[82:83]
	global_store_dwordx2 v[76:77], v[74:75], off
	v_add_u32_e32 v74, 0x8800, v82
	v_add_u32_e32 v78, v74, v133
	v_ashrrev_i32_e32 v79, 31, v78
	v_cvt_pk_bf16_f32 v76, v70, v71
	v_cvt_pk_bf16_f32 v77, v72, v73
	v_lshl_add_u64 v[78:79], v[78:79], 1, s[82:83]
	global_store_dwordx2 v[78:79], v[76:77], off
	s_and_saveexec_b64 s[46:47], s[44:45]
	s_cbranch_execz .LBB0_264
	v_mov_b32_e32 v75, v200
	v_add_u32_e32 v76, 0xb0, v130
	v_readlane_b32 s12, v254, 20
	v_ashrrev_i32_e32 v77, 31, v76
	v_readlane_b32 s13, v254, 21
	v_add_f32_e32 v70, v70, v75
	v_lshl_add_u64 v[76:77], v[76:77], 2, s[12:13]
	global_store_dword v[76:77], v70, off
	v_mov_b32_e32 v70, v201
	v_add_f32_e32 v75, v71, v70
	v_add_co_u32_e32 v70, vcc, 0x10000, v76
	s_nop 1
	v_addc_co_u32_e32 v71, vcc, 0, v77, vcc
	global_store_dword v[70:71], v75, off
	v_mov_b32_e32 v70, v202
	v_add_f32_e32 v72, v72, v70
	v_add_co_u32_e32 v70, vcc, 0x20000, v76
	s_nop 1
	v_addc_co_u32_e32 v71, vcc, 0, v77, vcc
	global_store_dword v[70:71], v72, off
	v_mov_b32_e32 v70, v203
	v_add_f32_e32 v72, v73, v70
	v_add_co_u32_e32 v70, vcc, 0x30000, v76
	s_nop 1
	v_addc_co_u32_e32 v71, vcc, 0, v77, vcc
	global_store_dword v[70:71], v72, off
